# I_SPLIT 0x9800 (9216 conversion items moved to phase 2 instead of 11776): margin check
# speedup vs baseline: 1.0002x; 1.0002x over previous
; __global__ void __launch_bounds__(NTHR, 2) mega_fwd(Args args) {
;     ...
;         if (PHM(0) && (ph == 0 || ph == 2)) {
;             constexpr int I_SPLIT = NITEMS;
;             int hb = bid, nh = G, a0 = 0, a1 = 384, i0 = 0, i1 = I_SPLIT; bool work = true;
;             if (ph == 2) {
;                 const int last = (1600 + G - 1) / G, rem = 1600 - (last - 1) * G; const bool all = (rem == G);
;                 work = all || bid >= rem; hb = all ? bid : bid - rem; nh = all ? G : G - rem; a0 = 384; a1 = 768; i0 = I_SPLIT; i1 = NITEMS;
;             }
;             if (work) {
.LBB0_368:
	s_cmp_eq_u32 s48, 0
	s_mov_b64 s[8:9], -1
	s_movk_i32 s2, 0x180
	s_cselect_b64 s[6:7], -1, 0
	s_mov_b32 s16, s56
	s_mov_b32 s26, s3
	s_mov_b32 s5, s48
	s_mov_b32 s17, s48
	s_mov_b32 s101, 0x9800
	s_andn2_b64 vcc, exec, s[6:7]
	s_cbranch_vccz .LBB0_371
	s_branch .LBB0_551

; __global__ void __launch_bounds__(NTHR, 2) mega_fwd(Args args) {
;     ...
;             if (ph == 2) {
;                 const int last = (1600 + G - 1) / G, rem = 1600 - (last - 1) * G; const bool all = (rem == G);
;                 work = all || bid >= rem; hb = all ? bid : bid - rem; nh = all ? G : G - rem; a0 = 384; a1 = 768; i0 = I_SPLIT; i1 = NITEMS;
.LBB0_370:
	v_readlane_b32 s8, v254, 32
	s_mov_b32 s17, 0x9800
	s_mov_b32 s101, 0xbc00
	s_movk_i32 s2, 0x300
	s_movk_i32 s5, 0x180
	v_readlane_b32 s16, v254, 34
	v_readlane_b32 s26, v254, 35
	v_readlane_b32 s9, v254, 33
	s_andn2_b64 vcc, exec, s[6:7]
	s_cbranch_vccnz .LBB0_551
